# GEMM phases: static s_setprio raise for the leading half-workgroup (waves 0-3)
# speedup vs baseline: 1.0005x; 1.0005x over previous
.LBB0_415:
	s_or_b64 exec, exec, s[20:21]
	s_cmp_eq_u32 s98, 2
	s_cselect_b64 s[8:9], -1, 0
	s_cmp_lg_u32 s98, 2
	s_cselect_b64 s[6:7], -1, 0
	v_mov_b32_e32 v2, v175
	s_and_b64 s[18:19], s[6:7], exec
	s_movk_i32 s5, 0x7e
	s_waitcnt lgkmcnt(0)
	s_barrier
	v_cmp_gt_u32_e32 vcc, 0x100, v175
	s_cbranch_vccz .Lg_noprio
	s_setprio 1
